# GEMM tile setup: scalar next-tile-exists test instead of two 64-bit VALU compares; accumulator zero-init interleaved with the unconditional scalar address arithmetic
# baseline (speedup 1.0000x reference)
.LBB0_173:
	s_add_i32 s92, s92, 1
	v_mov_b64_e32 v[2:3], 0
	v_mov_b64_e32 v[4:5], 0
	s_mul_i32 s7, s92, s55
	v_mov_b64_e32 v[6:7], 0
	v_mov_b64_e32 v[8:9], 0
	s_mul_hi_u32 s8, s92, s51
	v_mov_b64_e32 v[10:11], 0
	v_mov_b64_e32 v[12:13], 0
	s_add_i32 s8, s8, s7
	v_mov_b64_e32 v[14:15], 0
	v_mov_b64_e32 v[16:17], 0
	s_mul_i32 s7, s92, s51
	v_mov_b64_e32 v[18:19], 0
	v_mov_b64_e32 v[20:21], 0
	v_readlane_b32 s9, v253, 38
	s_add_u32 s24, s7, s9
	v_mov_b64_e32 v[22:23], 0
	v_mov_b64_e32 v[24:25], 0
	s_addc_u32 s25, s8, s72
	v_mov_b64_e32 v[26:27], 0
	v_mov_b64_e32 v[28:29], 0
	s_waitcnt lgkmcnt(0)
	s_cmp_lt_i32 s24, s68
	s_cselect_b64 s[8:9], -1, 0
	s_cbranch_scc0 .LBB0_175
	s_ashr_i32 s7, s24, 31
	s_lshr_b32 s7, s7, 29
	s_add_i32 s7, s24, s7
	s_ashr_i32 s11, s7, 3
	s_and_b32 s7, s7, -8
	s_sub_i32 s7, s24, s7
	s_lshr_b32 s13, s7, 31
	s_or_b32 s13, s18, s13
	s_mul_i32 s7, s13, s7
	s_add_i32 s7, s7, s11
	s_abs_i32 s13, s7
	s_mul_hi_u32 s24, s13, s41
	s_mul_i32 s25, s24, s50
	s_ashr_i32 s11, s7, 31
	s_sub_i32 s13, s13, s25
	s_xor_b32 s11, s11, s19
	s_add_i32 s25, s24, 1
	s_sub_i32 s28, s13, s50
	s_cmp_ge_u32 s13, s50
	s_cselect_b32 s24, s25, s24
	s_cselect_b32 s13, s28, s13
	s_add_i32 s25, s24, 1
	s_cmp_ge_u32 s13, s50
	s_cselect_b32 s13, s25, s24
	s_xor_b32 s13, s13, s11
	s_sub_i32 s11, s13, s11
	s_lshl_b32 s13, s11, 2
	s_sub_i32 s24, 0x90, s13
	s_min_i32 s24, s24, 4
	s_mul_i32 s11, s11, s48
	s_sub_i32 s7, s7, s11
	s_lshr_b32 s28, s7, 2
	s_and_b32 s7, s7, 3
	v_readlane_b32 s11, v254, 19
	s_add_i32 s11, s13, s11
	s_add_i32 s30, s11, s7
.LBB0_175:
	s_ashr_i32 s31, s30, 31
	v_mov_b64_e32 v[30:31], 0
	v_mov_b64_e32 v[32:33], 0
	v_mov_b64_e32 v[34:35], 0
	s_lshl_b64 s[24:25], s[30:31], 19
	v_mov_b64_e32 v[36:37], 0
	v_mov_b64_e32 v[38:39], 0
	v_mov_b64_e32 v[40:41], 0
	s_add_u32 s34, s62, s24
	v_mov_b64_e32 v[42:43], 0
	v_mov_b64_e32 v[44:45], 0
	v_mov_b64_e32 v[46:47], 0
	s_addc_u32 s35, s63, s25
	v_mov_b64_e32 v[48:49], 0
	v_mov_b64_e32 v[66:67], 0
	v_mov_b64_e32 v[68:69], 0
	s_and_b64 s[24:25], s[8:9], exec
	v_mov_b64_e32 v[70:71], 0
	v_mov_b64_e32 v[72:73], 0
	v_mov_b64_e32 v[74:75], 0
	s_cselect_b32 s7, s35, s15
	v_mov_b64_e32 v[76:77], 0
	v_mov_b64_e32 v[78:79], 0
	v_mov_b64_e32 v[80:81], 0
	s_cselect_b32 s11, s34, s14
	v_mov_b64_e32 v[82:83], 0
	v_mov_b64_e32 v[84:85], 0
	v_mov_b64_e32 v[86:87], 0
	s_ashr_i32 s29, s28, 31
	v_mov_b64_e32 v[88:89], 0
	v_mov_b64_e32 v[90:91], 0
	v_mov_b64_e32 v[92:93], 0
	s_lshl_b64 s[24:25], s[28:29], 19
	v_mov_b64_e32 v[94:95], 0
	v_mov_b64_e32 v[96:97], 0
	v_mov_b64_e32 v[98:99], 0
	v_readlane_b32 s13, v255, 7
	s_add_u32 s96, s13, s24
	v_mov_b64_e32 v[100:101], 0
	v_mov_b64_e32 v[102:103], 0
	v_mov_b64_e32 v[104:105], 0
	v_readlane_b32 s13, v255, 8
	s_addc_u32 s97, s13, s25
	v_mov_b64_e32 v[106:107], 0
	v_mov_b64_e32 v[108:109], 0
	v_mov_b64_e32 v[110:111], 0
	s_and_b64 s[24:25], s[8:9], exec
	v_mov_b64_e32 v[112:113], 0
	v_mov_b64_e32 v[114:115], 0
	v_mov_b64_e32 v[116:117], 0
	s_cselect_b32 s13, s97, s3
	v_mov_b64_e32 v[118:119], 0
	v_mov_b64_e32 v[120:121], 0
	v_mov_b64_e32 v[122:123], 0
	s_cselect_b32 s29, s96, s2
	v_mov_b64_e32 v[124:125], 0
	v_mov_b64_e32 v[126:127], 0
	v_mov_b64_e32 v[128:129], 0
	s_add_u32 s14, s14, 0x40080
	v_mov_b64_e32 v[130:131], 0
	v_mov_b64_e32 v[132:133], 0
	v_mov_b64_e32 v[134:135], 0
	s_addc_u32 s15, s15, 0
	v_mov_b64_e32 v[136:137], 0
	v_mov_b64_e32 v[138:139], 0
	v_mov_b64_e32 v[140:141], 0
	s_add_u32 s31, s2, 0x100
	v_mov_b64_e32 v[142:143], 0
	v_mov_b64_e32 v[144:145], 0
	s_addc_u32 s33, s3, 0
	s_mov_b32 s46, -2

.LBB0_647:
	s_add_i32 s39, s39, 1
	v_mov_b64_e32 v[2:3], 0
	v_mov_b64_e32 v[4:5], 0
	s_mul_i32 s8, s39, s55
	v_mov_b64_e32 v[6:7], 0
	v_mov_b64_e32 v[8:9], 0
	s_mul_hi_u32 s9, s39, s51
	v_mov_b64_e32 v[10:11], 0
	v_mov_b64_e32 v[12:13], 0
	s_add_i32 s9, s9, s8
	v_mov_b64_e32 v[14:15], 0
	v_mov_b64_e32 v[16:17], 0
	s_mul_i32 s8, s39, s51
	v_mov_b64_e32 v[18:19], 0
	v_mov_b64_e32 v[20:21], 0
	v_readlane_b32 s15, v253, 38
	s_add_u32 s18, s8, s15
	v_mov_b64_e32 v[22:23], 0
	v_mov_b64_e32 v[24:25], 0
	s_addc_u32 s19, s9, s72
	v_mov_b64_e32 v[26:27], 0
	v_mov_b64_e32 v[28:29], 0
	s_cmp_lt_i32 s18, s78
	s_cselect_b64 s[8:9], -1, 0
	s_cbranch_scc0 .LBB0_649
	s_ashr_i32 s14, s18, 31
	s_lshr_b32 s14, s14, 29
	s_add_i32 s14, s18, s14
	s_ashr_i32 s15, s14, 3
	s_and_b32 s14, s14, -8
	s_sub_i32 s14, s18, s14
	s_lshr_b32 s16, s14, 31
	s_or_b32 s16, s41, s16
	s_mul_i32 s14, s16, s14
	s_add_i32 s14, s14, s15
	s_ashr_i32 s15, s14, 31
	s_lshr_b32 s15, s15, 28
	s_add_i32 s15, s14, s15
	s_ashr_i32 s16, s15, 4
	s_lshl_b32 s16, s16, 2
	s_sub_i32 s17, s59, s16
	s_min_i32 s17, s17, 4
	s_and_b32 s15, s15, -16
	s_sub_i32 s15, s14, s15
	s_lshr_b32 s14, s15, 2
	s_and_b32 s15, s15, 3
	v_readlane_b32 s17, v254, 19
	s_add_i32 s16, s16, s17
	s_add_i32 s16, s16, s15
.LBB0_649:
	s_ashr_i32 s17, s16, 31
	v_mov_b64_e32 v[30:31], 0
	v_mov_b64_e32 v[32:33], 0
	v_mov_b64_e32 v[34:35], 0
	s_lshl_b64 s[18:19], s[16:17], 19
	v_mov_b64_e32 v[36:37], 0
	v_mov_b64_e32 v[38:39], 0
	v_mov_b64_e32 v[40:41], 0
	s_add_u32 s18, s84, s18
	v_mov_b64_e32 v[42:43], 0
	v_mov_b64_e32 v[44:45], 0
	v_mov_b64_e32 v[46:47], 0
	s_addc_u32 s19, s85, s19
	v_mov_b64_e32 v[48:49], 0
	v_mov_b64_e32 v[50:51], 0
	v_mov_b64_e32 v[52:53], 0
	s_and_b64 s[20:21], s[8:9], exec
	v_mov_b64_e32 v[54:55], 0
	v_mov_b64_e32 v[56:57], 0
	v_mov_b64_e32 v[58:59], 0
	s_cselect_b32 s17, s19, s5
	v_mov_b64_e32 v[60:61], 0
	v_mov_b64_e32 v[62:63], 0
	v_mov_b64_e32 v[64:65], 0
	s_cselect_b32 s25, s18, s4
	v_mov_b64_e32 v[66:67], 0
	v_mov_b64_e32 v[68:69], 0
	v_mov_b64_e32 v[70:71], 0
	s_ashr_i32 s15, s14, 31
	v_mov_b64_e32 v[72:73], 0
	v_mov_b64_e32 v[74:75], 0
	v_mov_b64_e32 v[76:77], 0
	s_lshl_b64 s[20:21], s[14:15], 19
	v_mov_b64_e32 v[78:79], 0
	v_mov_b64_e32 v[80:81], 0
	v_mov_b64_e32 v[82:83], 0
	s_add_u32 s20, s6, s20
	v_mov_b64_e32 v[84:85], 0
	v_mov_b64_e32 v[86:87], 0
	v_mov_b64_e32 v[88:89], 0
	s_addc_u32 s21, s7, s21
	v_mov_b64_e32 v[90:91], 0
	v_mov_b64_e32 v[92:93], 0
	v_mov_b64_e32 v[94:95], 0
	s_and_b64 s[26:27], s[8:9], exec
	v_mov_b64_e32 v[96:97], 0
	v_mov_b64_e32 v[98:99], 0
	v_mov_b64_e32 v[100:101], 0
	s_cselect_b32 s15, s21, s3
	v_mov_b64_e32 v[102:103], 0
	v_mov_b64_e32 v[104:105], 0
	v_mov_b64_e32 v[106:107], 0
	s_cselect_b32 s42, s20, s2
	v_mov_b64_e32 v[108:109], 0
	v_mov_b64_e32 v[110:111], 0
	v_mov_b64_e32 v[112:113], 0
	s_add_u32 s46, s2, 0x100
	v_mov_b64_e32 v[114:115], 0
	v_mov_b64_e32 v[116:117], 0
	v_mov_b64_e32 v[118:119], 0
	s_addc_u32 s47, s3, 0
	v_mov_b64_e32 v[120:121], 0
	v_mov_b64_e32 v[122:123], 0
	v_mov_b64_e32 v[124:125], 0
	s_mov_b32 s48, -2
	v_mov_b64_e32 v[126:127], 0
	v_mov_b64_e32 v[128:129], 0
	s_waitcnt lgkmcnt(0)

.LBB0_780:
	s_add_i32 s37, s37, 1
	v_mov_b64_e32 v[2:3], 0
	v_mov_b64_e32 v[4:5], 0
	s_mul_i32 s0, s37, s55
	v_mov_b64_e32 v[6:7], 0
	v_mov_b64_e32 v[8:9], 0
	s_mul_hi_u32 s1, s37, s51
	v_mov_b64_e32 v[10:11], 0
	v_mov_b64_e32 v[12:13], 0
	s_add_i32 s1, s1, s0
	v_mov_b64_e32 v[14:15], 0
	v_mov_b64_e32 v[16:17], 0
	s_mul_i32 s0, s37, s51
	v_mov_b64_e32 v[18:19], 0
	v_mov_b64_e32 v[20:21], 0
	v_readlane_b32 s15, v253, 38
	s_add_u32 s18, s0, s15
	v_mov_b64_e32 v[22:23], 0
	v_mov_b64_e32 v[24:25], 0
	s_addc_u32 s19, s1, s72
	v_mov_b64_e32 v[26:27], 0
	v_mov_b64_e32 v[28:29], 0
	s_cmp_lt_i32 s18, s8
	s_cselect_b64 s[0:1], -1, 0
	s_cbranch_scc0 .LBB0_782
	s_ashr_i32 s14, s18, 31
	s_lshr_b32 s14, s14, 29
	s_add_i32 s14, s18, s14
	s_ashr_i32 s15, s14, 3
	s_and_b32 s14, s14, -8
	s_sub_i32 s14, s18, s14
	s_cmp_lt_i32 s14, 0
	s_cselect_b32 s16, s30, s29
	s_mul_i32 s14, s16, s14
	s_add_i32 s14, s14, s15
	s_mul_hi_i32 s15, s14, 0x2e8ba2e9
	s_lshr_b32 s16, s15, 31
	s_ashr_i32 s15, s15, 4
	s_add_i32 s15, s15, s16
	s_lshl_b32 s16, s15, 2
	s_sub_i32 s17, s59, s16
	s_min_i32 s17, s17, 4
	s_mulk_i32 s15, 0x58
	s_sub_i32 s15, s14, s15
	s_lshr_b32 s14, s15, 2
	s_and_b32 s15, s15, 3
	v_readlane_b32 s17, v254, 19
	s_add_i32 s16, s16, s17
	s_add_i32 s16, s16, s15
.LBB0_782:
	s_ashr_i32 s17, s16, 31
	v_mov_b64_e32 v[30:31], 0
	v_mov_b64_e32 v[32:33], 0
	v_mov_b64_e32 v[34:35], 0
	s_lshl_b64 s[18:19], s[16:17], 19
	v_mov_b64_e32 v[36:37], 0
	v_mov_b64_e32 v[38:39], 0
	v_mov_b64_e32 v[40:41], 0
	s_add_u32 s18, s62, s18
	v_mov_b64_e32 v[42:43], 0
	v_mov_b64_e32 v[44:45], 0
	v_mov_b64_e32 v[46:47], 0
	s_addc_u32 s19, s63, s19
	v_mov_b64_e32 v[48:49], 0
	v_mov_b64_e32 v[50:51], 0
	v_mov_b64_e32 v[52:53], 0
	s_and_b64 s[20:21], s[0:1], exec
	v_mov_b64_e32 v[54:55], 0
	v_mov_b64_e32 v[56:57], 0
	v_mov_b64_e32 v[58:59], 0
	s_cselect_b32 s17, s19, s5
	v_mov_b64_e32 v[60:61], 0
	v_mov_b64_e32 v[62:63], 0
	v_mov_b64_e32 v[64:65], 0
	s_cselect_b32 s25, s18, s4
	v_mov_b64_e32 v[66:67], 0
	v_mov_b64_e32 v[68:69], 0
	v_mov_b64_e32 v[70:71], 0
	s_ashr_i32 s15, s14, 31
	v_mov_b64_e32 v[72:73], 0
	v_mov_b64_e32 v[74:75], 0
	v_mov_b64_e32 v[76:77], 0
	s_lshl_b64 s[20:21], s[14:15], 19
	v_mov_b64_e32 v[78:79], 0
	v_mov_b64_e32 v[80:81], 0
	v_mov_b64_e32 v[82:83], 0
	s_add_u32 s20, s6, s20
	v_mov_b64_e32 v[84:85], 0
	v_mov_b64_e32 v[86:87], 0
	v_mov_b64_e32 v[88:89], 0
	s_addc_u32 s21, s7, s21
	v_mov_b64_e32 v[90:91], 0
	v_mov_b64_e32 v[92:93], 0
	v_mov_b64_e32 v[94:95], 0
	s_and_b64 s[26:27], s[0:1], exec
	v_mov_b64_e32 v[96:97], 0
	v_mov_b64_e32 v[98:99], 0
	v_mov_b64_e32 v[100:101], 0
	s_cselect_b32 s15, s21, s3
	v_mov_b64_e32 v[102:103], 0
	v_mov_b64_e32 v[104:105], 0
	v_mov_b64_e32 v[106:107], 0
	s_cselect_b32 s41, s20, s2
	v_mov_b64_e32 v[108:109], 0
	v_mov_b64_e32 v[110:111], 0
	v_mov_b64_e32 v[112:113], 0
	s_add_u32 s4, s4, 0x40080
	v_mov_b64_e32 v[114:115], 0
	v_mov_b64_e32 v[116:117], 0
	v_mov_b64_e32 v[118:119], 0
	s_addc_u32 s5, s5, 0
	v_mov_b64_e32 v[120:121], 0
	v_mov_b64_e32 v[122:123], 0
	v_mov_b64_e32 v[124:125], 0
	s_add_u32 s42, s2, 0x100
	v_mov_b64_e32 v[126:127], 0
	v_mov_b64_e32 v[128:129], 0
	s_addc_u32 s46, s3, 0
	s_mov_b32 s47, -2

.LBB0_842:
	s_add_i32 s34, s34, 1
	v_mov_b64_e32 v[2:3], 0
	v_mov_b64_e32 v[4:5], 0
	s_mul_i32 s4, s34, s55
	v_mov_b64_e32 v[6:7], 0
	v_mov_b64_e32 v[8:9], 0
	s_mul_hi_u32 s5, s34, s51
	v_mov_b64_e32 v[10:11], 0
	v_mov_b64_e32 v[12:13], 0
	s_add_i32 s5, s5, s4
	v_mov_b64_e32 v[14:15], 0
	v_mov_b64_e32 v[16:17], 0
	s_mul_i32 s4, s34, s51
	v_mov_b64_e32 v[18:19], 0
	v_mov_b64_e32 v[20:21], 0
	v_readlane_b32 s8, v253, 38
	s_add_u32 s4, s4, s8
	v_mov_b64_e32 v[22:23], 0
	v_mov_b64_e32 v[24:25], 0
	s_addc_u32 s5, s5, s72
	v_mov_b64_e32 v[26:27], 0
	v_mov_b64_e32 v[28:29], 0
	s_cmp_lt_i32 s4, s78
	s_cselect_b64 s[8:9], -1, 0
	s_cbranch_scc0 .LBB0_844
	s_ashr_i32 s5, s4, 31
	s_lshr_b32 s5, s5, 29
	s_add_i32 s5, s4, s5
	s_ashr_i32 s14, s5, 3
	s_and_b32 s5, s5, -8
	s_sub_i32 s4, s4, s5
	s_lshr_b32 s5, s4, 31
	s_or_b32 s5, s35, s5
	s_mul_i32 s4, s5, s4
	s_add_i32 s4, s4, s14
	s_ashr_i32 s5, s4, 31
	s_lshr_b32 s5, s5, 28
	s_add_i32 s5, s4, s5
	s_ashr_i32 s14, s5, 4
	s_lshl_b32 s14, s14, 2
	s_sub_i32 s15, s59, s14
	s_min_i32 s15, s15, 4
	s_and_b32 s5, s5, -16
	s_sub_i32 s4, s4, s5
	s_lshr_b32 s36, s4, 2
	s_and_b32 s4, s4, 3
	v_readlane_b32 s5, v254, 19
	s_add_i32 s5, s14, s5
	s_add_i32 s37, s5, s4

.LBB0_848:
	s_add_u32 s17, s2, 0x100
	v_mov_b64_e32 v[30:31], 0
	v_mov_b64_e32 v[32:33], 0
	v_mov_b64_e32 v[34:35], 0
	s_addc_u32 s42, s3, 0
	v_mov_b64_e32 v[36:37], 0
	v_mov_b64_e32 v[38:39], 0
	v_mov_b64_e32 v[40:41], 0
	s_mov_b32 s46, -2
	v_mov_b64_e32 v[42:43], 0
	v_mov_b64_e32 v[44:45], 0
	v_mov_b64_e32 v[46:47], 0
	s_waitcnt lgkmcnt(0)
	v_mov_b64_e32 v[48:49], 0
	v_mov_b64_e32 v[50:51], 0
	v_mov_b64_e32 v[52:53], 0
	v_mov_b64_e32 v[54:55], 0
	v_mov_b64_e32 v[56:57], 0
	v_mov_b64_e32 v[58:59], 0
	v_mov_b64_e32 v[60:61], 0
	v_mov_b64_e32 v[62:63], 0
	v_mov_b64_e32 v[64:65], 0
	v_mov_b64_e32 v[66:67], 0
	v_mov_b64_e32 v[68:69], 0
	v_mov_b64_e32 v[70:71], 0
	v_mov_b64_e32 v[72:73], 0
	v_mov_b64_e32 v[74:75], 0
	v_mov_b64_e32 v[76:77], 0
	v_mov_b64_e32 v[78:79], 0
	v_mov_b64_e32 v[80:81], 0
	v_mov_b64_e32 v[82:83], 0
	v_mov_b64_e32 v[84:85], 0
	v_mov_b64_e32 v[86:87], 0
	v_mov_b64_e32 v[88:89], 0
	v_mov_b64_e32 v[90:91], 0
	v_mov_b64_e32 v[92:93], 0
	v_mov_b64_e32 v[94:95], 0
	v_mov_b64_e32 v[96:97], 0
	v_mov_b64_e32 v[98:99], 0
	v_mov_b64_e32 v[100:101], 0
	v_mov_b64_e32 v[102:103], 0
	v_mov_b64_e32 v[104:105], 0
	v_mov_b64_e32 v[106:107], 0
	v_mov_b64_e32 v[108:109], 0
	v_mov_b64_e32 v[110:111], 0
	v_mov_b64_e32 v[112:113], 0
	v_mov_b64_e32 v[114:115], 0
	v_mov_b64_e32 v[116:117], 0
	v_mov_b64_e32 v[118:119], 0
	v_mov_b64_e32 v[120:121], 0
	v_mov_b64_e32 v[122:123], 0
	v_mov_b64_e32 v[124:125], 0
	v_mov_b64_e32 v[126:127], 0
	v_mov_b64_e32 v[128:129], 0
